# speedup vs baseline: 1.0062x; 1.0040x over previous
; __global__ __launch_bounds__(512, 2)
; void hybrid_megakernel(Params p_in) {
;     ...
;         const bf16* proj = (const bf16*)(ws + WS_PROJ);
;         float* attO = (float*)(ws + WS_ATTO);
;         const unsigned* nrm = (const unsigned*)(ws + WS_NRM) + l * (NB * 32);
;         const int nitems = NB * 8 * 2 * (SEQ / 128);
;         const bool eightq = (G & 7) == 0;
;         const int xq = eightq ? (bid & 7) : 0;
;         unsigned* uctr = (unsigned*)(ws + WS_NRM) + 128 + l * 8 + xq;
.LBB0_145:
	s_mov_b32 s99, 0
	s_add_u32 s10, s54, 0x14000000
	s_addc_u32 s11, s55, 0
	s_add_u32 s14, s54, 0x2c000000
	s_addc_u32 s15, s55, 0
	s_add_u32 s16, s54, 0x5f108000
	s_addc_u32 s17, s55, 0
	s_lshl_b32 s0, s56, 6
	s_ashr_i32 s1, s0, 31
	s_lshl_b64 s[0:1], s[0:1], 2
	s_add_u32 s48, s16, s0
	s_addc_u32 s49, s17, s1
	s_and_b32 s2, s52, 7
	s_cmp_lg_u32 s2, 0
	v_readlane_b32 s0, v255, 21
	s_cselect_b64 s[66:67], -1, 0
	v_readlane_b32 s1, v255, 22
	s_mov_b32 s6, s0
	s_and_b32 s3, s0, 7
	s_lshl_b32 s0, s56, 3
	s_ashr_i32 s1, s0, 31
	s_lshl_b64 s[0:1], s[0:1], 2
	s_add_u32 s0, s54, s0
	s_addc_u32 s1, s55, s1
	s_cmp_eq_u32 s2, 0
	s_cselect_b32 s2, s3, 0
	s_movk_i32 s3, 0x100
	s_cselect_b32 s50, s3, 0x800
	s_lshl_b32 s2, s2, 2
	s_add_u32 s0, s0, s2
	s_addc_u32 s1, s1, 0
	s_add_u32 s68, s0, 0x5f108200
	s_addc_u32 s69, s1, 0
	s_lshl_b32 s0, s6, 5
	s_lshl_b32 s56, s56, 5
	s_bfe_u32 s51, s6, 0x10002
	s_bfe_u32 s57, s6, 0x20001
	s_and_b32 s61, s0, 32
	s_addk_i32 s56, 0x90
	v_and_b32_e32 v145, 63, v162
	v_lshlrev_b32_e32 v1, 3, v145
	v_lshlrev_b32_e32 v4, 4, v145
	s_cmp_lg_u32 0, -1
	v_and_b32_e32 v2, 24, v1
	v_and_b32_e32 v5, 0xc0, v4
	v_lshlrev_b32_e32 v6, 1, v162
	s_cselect_b32 s0, 0, 0
	v_and_b32_e32 v6, 32, v6
	v_and_b32_e32 v1, 0x100, v1
	v_add3_u32 v2, v5, s0, v2
	v_bfe_u32 v163, v162, 5, 1
	v_add3_u32 v167, v2, v6, v1
	v_lshlrev_b32_e32 v1, 4, v162
	v_and_b32_e32 v175, 24, v0
	v_and_b32_e32 v149, 31, v162
	v_lshlrev_b32_e32 v165, 4, v163
	v_and_b32_e32 v1, 0x70, v1
	v_bitop3_b32 v2, v163, v162, 7 bitop3:0x78
	s_movk_i32 s0, 0x60
	v_and_or_b32 v0, v162, 32, v175
	v_lshlrev_b32_e32 v164, 2, v163
	v_lshlrev_b32_e32 v169, 4, v2
	v_bitop3_b32 v170, v165, v1, 32 bitop3:0x36
	v_bitop3_b32 v171, v165, v1, 64 bitop3:0x36
	v_bitop3_b32 v172, v165, v1, s0 bitop3:0x36
	v_bfe_u32 v1, v144, 2, 2
	v_lshrrev_b32_e32 v2, 1, v144
	v_lshlrev_b32_e32 v176, 1, v0
	v_lshlrev_b32_e32 v0, 2, v149
	s_movk_i32 s94, 0x2000
	v_cmp_eq_u32_e64 s[4:5], 0, v144
	v_cmp_gt_u32_e64 s[6:7], 32, v145
	v_cvt_f32_ubyte0_e32 v166, v164
	v_add_u32_e32 v168, 0, v4
	v_and_b32_e32 v173, 15, v162
	v_and_or_b32 v174, v2, 8, v1
	v_lshl_or_b32 v177, v163, 9, v149
	v_lshl_or_b32 v178, v163, 7, v0
	v_lshlrev_b32_e32 v146, 1, v0
	s_branch .LBB0_148

; __device__ __forceinline__ unsigned rfl(unsigned v) { return (unsigned)__builtin_amdgcn_readfirstlane((int)v); }
; __global__ __launch_bounds__(512, 2)
; void hybrid_megakernel(Params p_in) {
;     ...
;         for (;;) {
;           __syncthreads();
;           if (tid == 0) *(volatile unsigned*)(shm + A3_X + 8192) = atomicAdd(uctr, 1u);
;           __syncthreads();
;           const int item = (int)rfl(*(volatile unsigned*)(shm + A3_X + 8192));
;           __syncthreads();
;           if (item >= (eightq ? nitems / 8 : nitems)) break;
.LBB0_148:
	s_waitcnt vmcnt(0) lgkmcnt(0)
	s_barrier
	s_and_saveexec_b64 s[0:1], s[4:5]
	s_cbranch_execz .LBB0_152
	s_cmp_eq_u32 s99, 0
	s_cbranch_scc1 .Lq_fetch
	v_mov_b32_e32 v1, v254
	v_mov_b32_e32 v0, 0
	s_mov_b64 s[2:3], exec
	s_branch .LBB0_151
.Lq_fetch:
	s_mov_b64 s[8:9], exec
	v_mbcnt_lo_u32_b32 v0, s8, 0
	v_mbcnt_hi_u32_b32 v0, s9, v0
	v_cmp_eq_u32_e32 vcc, 0, v0
	s_and_saveexec_b64 s[2:3], vcc
	s_cbranch_execz .LBB0_151
	s_bcnt1_i32_b64 s8, s[8:9]
	v_mov_b32_e32 v1, s8
	global_atomic_add v1, v3, v1, s[68:69] sc0

; __device__ __forceinline__ unsigned rfl(unsigned v) { return (unsigned)__builtin_amdgcn_readfirstlane((int)v); }
; __global__ __launch_bounds__(512, 2)
; void hybrid_megakernel(Params p_in) {
;     ...
;           const float slope = exp2f(-(float)(h + 1));
;           const float q2 = __uint_as_float(rfl(nrm[b * 32 + h * 2 + c])), k2 = __uint_as_float(rfl(nrm[b * 32 + 16 + h * 2 + c]));
;           const float Bnd = sqrtf(q2 * k2) * ASCALE * 1.002f + 0.05f;
;           const float nsf = __uint_as_float(rfl(((const unsigned*)(ws + WS_NRM))[144 + l * (NB * 16) + b * 16 + h * 2 + c]));
;           const float lowb = fminf(nsf * ASCALE * 1.002f + 0.05f, Bnd);
.LBB0_157:
	s_sub_i32 s0, 8, s8
	v_cvt_f32_i32_e32 v0, s0
	s_mov_b32 s0, 0x42fc0000
	v_mov_b32_e32 v1, 0x42800000
	s_and_b32 s63, s9, 1
	v_cmp_lt_f32_e32 vcc, s0, v0
	s_sub_i32 s1, 7, s8
	s_and_b64 s[8:9], vcc, exec
	v_cndmask_b32_e32 v1, 0, v1, vcc
	v_sub_f32_e32 v0, v1, v0
	v_exp_f32_e32 v0, v0
	s_cselect_b32 s0, 0xffffffc0, 0
	s_lshl_b32 s3, s1, 1
	v_mov_b32_e32 v153, v3
	v_ldexp_f32 v0, v0, s0
	s_lshl_b32 s0, s38, 5
	s_add_i32 s0, s0, s3
	s_or_b32 s8, s0, s63
	s_ashr_i32 s9, s8, 31
	s_lshl_b64 s[28:29], s[8:9], 2
	s_add_u32 s28, s48, s28
	s_addc_u32 s29, s49, s29
	global_load_dword v1, v3, s[28:29]
	s_ashr_i32 s9, s0, 31
	s_lshl_b64 s[8:9], s[8:9], 2
	s_add_u32 s8, s48, s8
	s_addc_u32 s9, s49, s9
	global_load_dword v2, v3, s[8:9] offset:64
	v_mov_b32_e32 v157, v3
	s_movk_i32 s95, 0x6000
	s_waitcnt vmcnt(0)
	v_readfirstlane_b32 s28, v1
	v_readfirstlane_b32 s0, v2
	s_nop 1
	v_mov_b32_e32 v1, s0
	v_mul_f32_e32 v1, s28, v1
	s_mov_b32 s0, 0xf800000
	v_cmp_gt_f32_e32 vcc, s0, v1
	v_mul_f32_e32 v2, 0x4f800000, v1
	s_lshl_b32 s0, s38, 4
	v_cndmask_b32_e32 v1, v1, v2, vcc
	v_sqrt_f32_e32 v2, v1
	s_add_i32 s0, s56, s0
	s_add_i32 s0, s0, s3
	v_add_u32_e32 v4, -1, v2
	v_fma_f32 v5, -v4, v2, v1
	v_cmp_ge_f32_e64 s[8:9], 0, v5
	v_add_u32_e32 v5, 1, v2
	s_nop 0
	v_cndmask_b32_e64 v4, v2, v4, s[8:9]
	v_fma_f32 v2, -v5, v2, v1
	v_cmp_lt_f32_e64 s[8:9], 0, v2
	s_nop 1
	v_cndmask_b32_e64 v2, v4, v5, s[8:9]
	v_mul_f32_e32 v4, 0x37800000, v2
	s_or_b32 s8, s0, s63
	v_cndmask_b32_e32 v2, v2, v4, vcc
	v_mov_b32_e32 v4, 0x260
	s_ashr_i32 s9, s8, 31
	v_cmp_class_f32_e32 vcc, v1, v4
	s_lshl_b64 s[8:9], s[8:9], 2
	s_add_u32 s8, s16, s8
	v_cndmask_b32_e32 v1, v2, v1, vcc
	v_mul_f32_e32 v1, 0x3db504f3, v1
	s_addc_u32 s9, s17, s9
	v_fmamk_f32 v20, v1, 0x3f804189, v195
	s_barrier
; __device__ __forceinline__ void attn_body3(const bf16* __restrict__ Qb, const bf16* __restrict__ Kh, const bf16* __restrict__ Vh,
;                                            bf16* __restrict__ Ob, int seq, int qpos0, float slS, float mraw, char* lds, const int tid) {
;   const int wid = __builtin_amdgcn_readfirstlane(tid >> 6), lane = tid & 63, r32 = lane & 31, hi = lane >> 5;
;   const int pair = wid & 3, role = wid >> 2;
;   constexpr float C = ASCALE * 1.4426950408889634f;
;   f32x16 o[4] = {}; bf16x8 qr[8]; float lsum = 0.f;
;   const int qw0 = qpos0 + pair * QBLK;
;   const float qposf = (float)(qw0 + r32), hi4 = 4.f * (float)hi + 32.f * (float)role;
;   unsigned qa0, qa1, kj0;
;   { const float a1 = bf_lo(cvtpk(slS, 0.f) & 0xffffu), r1 = slS - a1, a2 = bf_lo(cvtpk(r1, 0.f) & 0xffffu), a3 = r1 - a2;
;     const unsigned u12 = cvtpk(a1, a2), u3 = cvtpk(a3, 0.f) & 0xffffu;
;     const unsigned j0 = __float_as_uint((float)(r32 + 32 * role)) >> 16;
;     qa0 = hi ? 0u : u12; qa1 = hi ? 0u : u3; kj0 = hi ? 0u : (j0 | (j0 << 16)); }
;   { const unsigned qoff = (unsigned)((pair * QBLK + r32) * LDQ + hi * 8) * 2u;
; #pragma unroll
;     for (int d0 = 0; d0 < 8; ++d0) qr[d0] = *reinterpret_cast<const bf16x8*>((const char*)Qb + qoff + d0 * 32); }
;   const int vb0 = (int)(uintptr_t)(lds + A3_V) + role * 16384 + v_rd_base(lane);
; __global__ __launch_bounds__(512, 2)
; void hybrid_megakernel(Params p_in) {
;     ...
;           const float Wn = (Bnd + lowb + 104.f) / slope;
;           int t_lo = (int)floorf(fmaxf((float)(qb * 128) - Wn, 0.f) * (1.f / 64.f)) & ~1;
;           int t_hi = (int)fminf(((float)(qb * 128 + 127) + Wn) * (1.f / 64.f) + 1.f, (float)(SEQ / KVBLK));
;           t_hi = min((t_hi + 1) & ~1, SEQ / KVBLK);
;           t_lo = __builtin_amdgcn_readfirstlane(t_lo); t_hi = __builtin_amdgcn_readfirstlane(t_hi);
;           const bf16* Qb = proj + ((long)b * SEQ + qb * 128) * INC + OFF_Q + h * 256 + c * 128;
;           const bf16* Kh = proj + ((long)b * SEQ + t_lo * KVBLK) * INC + OFF_K + h * 256 + c * 128;
;           const bf16* Vh = proj + ((long)b * SEQ + t_lo * KVBLK) * INC + OFF_V + h * 256;
;           bf16* Ob = (bf16*)attO + (long)c * NTOK * 2048 + ((long)b * SEQ + qb * 128) * 2048 + h * 256;
;           __syncthreads();
;           attn_body3(Qb, Kh, Vh, Ob, (t_hi - t_lo) * KVBLK, qb * 128 - t_lo * KVBLK, slope / ASCALE, Bnd / ASCALE, shm, tid);
	s_waitcnt vmcnt(0)
	v_mov_b32_e32 v1, 0x42b20000
	v_div_scale_f32 v2, s[8:9], v0, v0, v1
	v_rcp_f32_e32 v4, v2
	s_lshl_b32 s0, s2, 7
	s_or_b32 s2, s0, 0x7f
	s_lshl_b64 s[8:9], s[38:39], 13
	v_fma_f32 v5, -v2, v4, 1.0
	v_fmac_f32_e32 v4, v5, v4
	v_div_scale_f32 v5, vcc, v1, v0, v1
	v_mul_f32_e32 v6, v5, v4
	v_fma_f32 v7, -v2, v6, v5
	v_fmac_f32_e32 v6, v7, v4
	v_fma_f32 v2, -v2, v6, v5
	v_div_fmas_f32 v2, v2, v4, v6
	v_div_fixup_f32 v1, v2, v0, v1
	v_cvt_f32_u32_e32 v2, s0
	v_cvt_f32_u32_e32 v4, s2
	s_mov_b32 s2, 0x3c800000
	v_sub_f32_e32 v2, v2, v1
	v_max_f32_e32 v2, 0, v2
	v_mul_f32_e32 v2, 0x3c800000, v2
	v_floor_f32_e32 v2, v2
	v_add_f32_e32 v1, v1, v4
	v_fma_f32 v1, v1, s2, 1.0
	v_readfirstlane_b32 s2, v2
	v_min_f32_e32 v1, 0x43000000, v1
	v_cvt_i32_f32_e32 v1, v1
	v_cvt_i32_f32_e32 v2, s2
	v_add_u32_e32 v1, 1, v1
	v_readfirstlane_b32 s2, v2
	s_and_b32 s28, s2, -2
	s_add_u32 s70, s8, s0
	s_addc_u32 s71, s9, 0
	s_mul_i32 s2, s71, 0x6000
	s_mul_hi_u32 s3, s70, 0x6000
	s_add_i32 s3, s3, s2
	s_mul_i32 s2, s70, 0x6000
	s_add_u32 s38, s10, s2
	s_addc_u32 s74, s11, s3
	s_lshl_b32 s2, s1, 8
	s_ashr_i32 s3, s2, 31
	s_lshl_b64 s[72:73], s[2:3], 1
	s_add_u32 s1, s38, s72
	s_addc_u32 s3, s74, s73
	s_lshl_b32 s38, s63, 8
	s_add_u32 s2, s1, s38
	s_addc_u32 s3, s3, 0
	s_lshl_b32 s1, s28, 6
	s_ashr_i32 s74, s1, 31
	s_add_u32 s8, s8, s1
	s_addc_u32 s9, s9, s74
	s_mulk_i32 s9, 0x6000
	s_mul_hi_u32 s74, s8, 0x6000
	s_add_i32 s74, s74, s9
	s_mulk_i32 s8, 0x6000
	s_add_u32 s8, s10, s8
	s_addc_u32 s9, s11, s74
	s_add_u32 s8, s8, s72
	s_addc_u32 s9, s9, s73
	s_add_u32 s38, s8, s38
	s_addc_u32 s75, s9, 0
	v_and_b32_e32 v1, -2, v1
	s_add_u32 s74, s38, 0x1000
	v_min_i32_e32 v1, 0x80, v1
	s_addc_u32 s75, s75, 0
	v_readfirstlane_b32 s29, v1
	s_add_u32 s76, s8, 0x2000
	s_addc_u32 s77, s9, 0
	s_sub_i32 s80, s29, s28
	s_mov_b32 s28, 0x3db504f3
	v_div_scale_f32 v1, s[8:9], s28, s28, v0
	v_rcp_f32_e32 v2, v1
	v_readfirstlane_b32 s8, v144
	s_ashr_i32 s79, s8, 6
	s_and_b32 s81, s79, 3
	v_fma_f32 v4, -v1, v2, 1.0
	v_fmac_f32_e32 v2, v4, v2
	v_div_scale_f32 v4, vcc, v0, s28, v0
	v_mul_f32_e32 v5, v4, v2
	v_fma_f32 v6, -v1, v5, v4
	v_fmac_f32_e32 v5, v6, v2
	v_fma_f32 v1, -v1, v5, v4
	v_div_fmas_f32 v1, v1, v2, v5
	v_div_fixup_f32 v148, v1, s28, v0
	v_cvt_pk_bf16_f32 v0, v148, v3
	s_lshl_b32 s78, s81, 5
	v_lshlrev_b32_e32 v0, 16, v0
	v_sub_f32_e32 v1, v148, v0
	v_cvt_pk_bf16_f32 v2, v1, v3
	s_ashr_i32 s38, s8, 8
	v_lshlrev_b32_e32 v2, 16, v2
	v_sub_f32_e32 v1, v1, v2
	v_cvt_pk_bf16_f32 v0, v0, v2
	v_or_b32_e32 v2, s78, v149
	v_mul_u32_u24_e32 v2, 0x6000, v2
	v_or_b32_e32 v2, v2, v165
	v_cvt_pk_bf16_f32 v1, v1, v3
	global_load_dwordx4 v[96:99], v2, s[2:3]
	global_load_dwordx4 v[100:103], v2, s[2:3] offset:32
	global_load_dwordx4 v[104:107], v2, s[2:3] offset:64
	global_load_dwordx4 v[108:111], v2, s[2:3] offset:96
	global_load_dwordx4 v[112:115], v2, s[2:3] offset:128
	global_load_dwordx4 v[116:119], v2, s[2:3] offset:160
	global_load_dwordx4 v[120:123], v2, s[2:3] offset:192
	global_load_dwordx4 v[124:127], v2, s[2:3] offset:224
	s_lshl_b32 s2, s79, 7
	v_or_b32_e32 v2, s2, v145
	s_ashr_i32 s2, s2, 4
	s_and_b32 s3, s2, 0x7fff0
	s_lshr_b32 s2, s2, 1
	v_or_b32_e32 v4, s3, v174
	v_and_or_b32 v4, s2, 4, v4
	v_ashrrev_i32_e32 v5, 4, v2
	s_movk_i32 s2, 0x6000
	v_mul_lo_u32 v6, v5, s2
	v_bitop3_b32 v5, v5, v173, 3 bitop3:0x6c
	v_or_b32_e32 v2, 64, v2
	v_lshl_or_b32 v150, v5, 4, v6
	v_ashrrev_i32_e32 v5, 4, v2
	v_mul_lo_u32 v6, v5, s2
	s_movk_i32 s2, 0x60
	v_and_or_b32 v2, v2, s2, v175
	s_lshl_b32 s2, s79, 11
	s_add_i32 s83, s2, 0
	s_add_i32 s84, s83, 0x18000
	v_bitop3_b32 v5, v5, v173, 7 bitop3:0x6c
	s_mov_b32 m0, s84
	s_add_i32 s85, s83, 0x18400
	v_mul_u32_u24_e32 v4, 0x6000, v4
	v_lshl_or_b32 v154, v5, 4, v6
	global_load_lds_dwordx4 v150, s[74:75]
	s_mov_b32 m0, s85
	v_or_b32_e32 v152, v4, v176
	global_load_lds_dwordx4 v154, s[74:75]
	s_mov_b32 m0, s83
	v_lshl_or_b32 v156, v2, 1, v4
	v_lshl_add_u64 v[4:5], s[76:77], 0, v[152:153]
	global_load_lds_dwordx4 v152, s[76:77]
	s_add_i32 m0, s83, 0x400
	v_lshl_add_u64 v[6:7], s[76:77], 0, v[156:157]
	global_load_lds_dwordx4 v156, s[76:77]
	v_lshl_add_u64 v[4:5], v[4:5], 0, s[42:43]
	s_add_i32 m0, s83, 0x4000
	s_lshl_b32 s82, s38, 5
	global_load_lds_dwordx4 v[4:5], off
	v_lshl_add_u64 v[4:5], v[6:7], 0, s[42:43]
	s_add_i32 m0, s83, 0x4400
	v_or_b32_e32 v147, s82, v149
	global_load_lds_dwordx4 v[4:5], off
	v_lshl_add_u32 v179, s81, 12, v168
	v_lshl_add_u32 v180, s38, 14, v167
	s_cmp_lt_i32 s80, 1
	s_waitcnt vmcnt(4) lgkmcnt(0)
	s_barrier
	s_cbranch_scc1 .LBB0_186
	v_mov_b32_e32 v151, v3
	v_mov_b32_e32 v155, v3
	s_lshl_b32 s29, s80, 6
	s_cmpk_lt_u32 s29, 0x80
	s_cbranch_scc1 .LBB0_160
	s_add_u32 s2, s76, 0x180000
	s_addc_u32 s3, s77, 0
	s_add_u32 s8, s74, 0x180000
	s_addc_u32 s9, s75, 0
	v_lshl_add_u64 v[4:5], s[8:9], 0, v[150:151]
	s_add_i32 m0, s83, 0x1c000
	s_nop 0
	global_load_lds_dwordx4 v[4:5], off
	v_lshl_add_u64 v[4:5], s[8:9], 0, v[154:155]
	s_add_i32 m0, s83, 0x1c400
	s_nop 0
	global_load_lds_dwordx4 v[4:5], off
	v_lshl_add_u64 v[4:5], s[2:3], 0, v[152:153]
	s_add_i32 m0, s83, 0x8000
	s_nop 0
	global_load_lds_dwordx4 v[4:5], off
	s_add_i32 m0, s83, 0x8400
	v_lshl_add_u64 v[4:5], s[2:3], 0, v[156:157]
	s_add_u32 s2, s76, 0x180100
	s_addc_u32 s3, s77, 0
	global_load_lds_dwordx4 v[4:5], off
	v_lshl_add_u64 v[4:5], s[2:3], 0, v[152:153]
	s_add_i32 m0, s83, 0xc000
	s_nop 0
	global_load_lds_dwordx4 v[4:5], off
	v_lshl_add_u64 v[4:5], s[2:3], 0, v[156:157]
	s_add_i32 m0, s83, 0xc400
	s_nop 0
	global_load_lds_dwordx4 v[4:5], off

.Lattn_head:
.LBB0_174:
	ds_read_b128 v[8:11], v206 offset:0
	s_add_i32 s91, s82, s89
	v_lshl_add_u32 v208, s0, 15, v180
	ds_read_b128 v[4:7], v206 offset:0x400
	s_add_i32 s28, s89, 0xffffff80
	s_add_i32 s2, s91, 0xffffff80
	s_add_i32 s0, s91, 0xffffff9f
	ds_read_b64_tr_b16 v[136:137], v208 offset:0
	s_cmp_gt_i32 s0, s86
	ds_read_b64_tr_b16 v[138:139], v208 offset:0x800
	s_cselect_b64 s[8:9], -1, 0
	s_cmp_lt_i32 s2, s87
	ds_read_b64_tr_b16 v[140:141], v208 offset:0x200
	s_cselect_b64 s[0:1], -1, 0
	s_cmp_ge_i32 s2, s87
	ds_read_b64_tr_b16 v[142:143], v208 offset:0xa00
	s_cselect_b64 s[2:3], -1, 0
	ds_read_b64_tr_b16 v[12:13], v208 offset:0x400
	s_and_b64 vcc, s[8:9], s[2:3]
	ds_read_b64_tr_b16 v[14:15], v208 offset:0xc00
	v_cndmask_b32_e32 v0, 0, v183, vcc
	v_cndmask_b32_e32 v1, 0, v184, vcc
	ds_read_b64_tr_b16 v[132:133], v208 offset:0x600
	v_cndmask_b32_e64 v0, v181, v0, s[8:9]
	v_cndmask_b32_e64 v1, v182, v1, s[8:9]
	v_mov_b32_e32 v2, v3
	ds_read_b64_tr_b16 v[134:135], v208 offset:0xe00
	ds_read_b128 v[210:213], v186 offset:0
	ds_read_b128 v[214:217], v187 offset:0
	ds_read_b128 v[218:221], v188 offset:0
	ds_read_b128 v[222:225], v189 offset:0
	s_nop 1
	v_mfma_f32_32x32x16_bf16 v[80:95], v[128:131], v[0:3], 0
	s_add_i32 m0, s83, 0x1c000
	s_nop 0
	global_load_lds_dwordx4 v242, s[74:75]
	s_waitcnt lgkmcnt(3)
	v_mfma_f32_32x32x16_bf16 v[80:95], v[210:213], v[96:99], v[80:95]
	ds_read_b128 v[210:213], v186 offset:0x80
	s_add_i32 m0, s83, 0x1c400
	s_nop 0
	global_load_lds_dwordx4 v243, s[74:75]
	s_waitcnt lgkmcnt(3)
	v_mfma_f32_32x32x16_bf16 v[80:95], v[214:217], v[100:103], v[80:95]
	ds_read_b128 v[214:217], v187 offset:0x80
	s_waitcnt lgkmcnt(3)
	v_mfma_f32_32x32x16_bf16 v[80:95], v[218:221], v[104:107], v[80:95]
	ds_read_b128 v[218:221], v188 offset:0x80
	s_waitcnt lgkmcnt(3)
	v_mfma_f32_32x32x16_bf16 v[80:95], v[222:225], v[108:111], v[80:95]
	ds_read_b128 v[222:225], v189 offset:0x80
	s_waitcnt lgkmcnt(3)
	v_mfma_f32_32x32x16_bf16 v[80:95], v[210:213], v[112:115], v[80:95]
	s_waitcnt lgkmcnt(2)
	v_mfma_f32_32x32x16_bf16 v[80:95], v[214:217], v[116:119], v[80:95]
	s_waitcnt lgkmcnt(1)
	v_mfma_f32_32x32x16_bf16 v[80:95], v[218:221], v[120:123], v[80:95]
	s_waitcnt lgkmcnt(0)
	v_mfma_f32_32x32x16_bf16 v[80:95], v[222:225], v[124:127], v[80:95]
	v_cvt_f32_u32_e32 v0, s28
	s_and_b64 s[2:3], s[8:9], s[0:1]
	s_mov_b64 s[0:1], -1
	s_andn2_b64 vcc, exec, s[2:3]
	v_sub_f32_e32 v1, v185, v0
	s_cbranch_vccz .LBB0_176
	v_cndmask_b32_e64 v0, -v148, v148, s[8:9]
	v_mul_f32_e32 v0, v1, v0
	s_mov_b64 s[0:1], 0
.LBB0_176:
	s_and_b64 vcc, exec, s[0:1]
	s_cbranch_vccnz .Ldiag_a
.LBB0_178:
	v_sub_f32_e32 v0, v0, v203
	v_mul_f32_e32 v0, 0x3e0293ee, v0
	s_waitcnt lgkmcnt(4)
	v_mfma_f32_32x32x16_bf16 v[32:47], v[8:11], v[136:139], v[32:47]
	ds_read_b64_tr_b16 v[136:137], v208 offset:0x1000
	ds_read_b64_tr_b16 v[138:139], v208 offset:0x1800
	v_fmamk_f32 v1, v80, 0x3e0293ee, v0
	v_exp_f32_e32 v209, v1
	v_mfma_f32_32x32x16_bf16 v[16:31], v[8:11], v[140:143], v[16:31]
	ds_read_b64_tr_b16 v[140:141], v208 offset:0x1200
	ds_read_b64_tr_b16 v[142:143], v208 offset:0x1a00
	v_fmamk_f32 v1, v81, 0x3e0293ee, v0
	v_exp_f32_e32 v210, v1
	s_waitcnt lgkmcnt(4)
	v_mfma_f32_32x32x16_bf16 v[64:79], v[8:11], v[12:15], v[64:79]
	v_fmamk_f32 v1, v82, 0x3e0293ee, v0
	v_exp_f32_e32 v211, v1
	v_mfma_f32_32x32x16_bf16 v[48:63], v[8:11], v[132:135], v[48:63]
	s_mov_b32 m0, s97
	s_nop 0
	global_load_lds_dwordx4 v244, s[76:77]
	ds_read_b128 v[8:11], v206 offset:0x800
	ds_read_b64_tr_b16 v[12:13], v208 offset:0x1400
	ds_read_b64_tr_b16 v[14:15], v208 offset:0x1c00
	ds_read_b64_tr_b16 v[132:133], v208 offset:0x1600
	ds_read_b64_tr_b16 v[134:135], v208 offset:0x1e00
	v_fmamk_f32 v1, v83, 0x3e0293ee, v0
	v_exp_f32_e32 v212, v1
	s_waitcnt lgkmcnt(5)
	v_mfma_f32_32x32x16_bf16 v[32:47], v[4:7], v[136:139], v[32:47]
	ds_read_b64_tr_b16 v[136:137], v208 offset:0x2000
	ds_read_b64_tr_b16 v[138:139], v208 offset:0x2800
	v_fmamk_f32 v1, v84, 0x3e0293ee, v0
	v_exp_f32_e32 v213, v1
	v_mfma_f32_32x32x16_bf16 v[16:31], v[4:7], v[140:143], v[16:31]
	s_add_i32 m0, s97, 0x400
	s_nop 0
	global_load_lds_dwordx4 v245, s[76:77]
	ds_read_b64_tr_b16 v[140:141], v208 offset:0x2200
	ds_read_b64_tr_b16 v[142:143], v208 offset:0x2a00
	v_fmamk_f32 v1, v85, 0x3e0293ee, v0
	v_exp_f32_e32 v214, v1
	s_waitcnt lgkmcnt(4)
	v_mfma_f32_32x32x16_bf16 v[64:79], v[4:7], v[12:15], v[64:79]
	v_fmamk_f32 v1, v86, 0x3e0293ee, v0
	v_exp_f32_e32 v215, v1
	v_mfma_f32_32x32x16_bf16 v[48:63], v[4:7], v[132:135], v[48:63]
	s_add_i32 m0, s97, 0x4000
	s_nop 0
	global_load_lds_dwordx4 v246, s[76:77]
	ds_read_b128 v[4:7], v206 offset:0xc00
	ds_read_b64_tr_b16 v[12:13], v208 offset:0x2400
	ds_read_b64_tr_b16 v[14:15], v208 offset:0x2c00
	ds_read_b64_tr_b16 v[132:133], v208 offset:0x2600
	ds_read_b64_tr_b16 v[134:135], v208 offset:0x2e00
	v_fmamk_f32 v1, v87, 0x3e0293ee, v0
	v_exp_f32_e32 v216, v1
	s_waitcnt lgkmcnt(5)
	v_mfma_f32_32x32x16_bf16 v[32:47], v[8:11], v[136:139], v[32:47]
	ds_read_b64_tr_b16 v[136:137], v208 offset:0x3000
	ds_read_b64_tr_b16 v[138:139], v208 offset:0x3800
	v_fmamk_f32 v1, v88, 0x3e0293ee, v0
	v_exp_f32_e32 v217, v1
	v_mfma_f32_32x32x16_bf16 v[16:31], v[8:11], v[140:143], v[16:31]
	s_add_i32 m0, s97, 0x4400
	s_nop 0
	global_load_lds_dwordx4 v247, s[76:77]
	ds_read_b64_tr_b16 v[140:141], v208 offset:0x3200
	ds_read_b64_tr_b16 v[142:143], v208 offset:0x3a00
	v_fmamk_f32 v1, v89, 0x3e0293ee, v0
	v_exp_f32_e32 v218, v1
	s_waitcnt lgkmcnt(4)
	v_mfma_f32_32x32x16_bf16 v[64:79], v[8:11], v[12:15], v[64:79]
	v_fmamk_f32 v1, v90, 0x3e0293ee, v0
	v_exp_f32_e32 v219, v1
	v_mfma_f32_32x32x16_bf16 v[48:63], v[8:11], v[132:135], v[48:63]
	ds_read_b64_tr_b16 v[8:9], v208 offset:0x3400
	ds_read_b64_tr_b16 v[10:11], v208 offset:0x3c00
	ds_read_b64_tr_b16 v[12:13], v208 offset:0x3600
	ds_read_b64_tr_b16 v[14:15], v208 offset:0x3e00
	v_fmamk_f32 v1, v91, 0x3e0293ee, v0
	v_exp_f32_e32 v220, v1
	s_waitcnt lgkmcnt(4)
	v_mfma_f32_32x32x16_bf16 v[32:47], v[4:7], v[136:139], v[32:47]
	v_fmamk_f32 v1, v92, 0x3e0293ee, v0
	v_exp_f32_e32 v221, v1
	v_fmamk_f32 v1, v93, 0x3e0293ee, v0
	v_exp_f32_e32 v222, v1
	s_waitcnt lgkmcnt(0)
	v_mfma_f32_32x32x16_bf16 v[16:31], v[4:7], v[140:143], v[16:31]
	v_fmamk_f32 v1, v94, 0x3e0293ee, v0
	v_fmac_f32_e32 v0, 0x3e0293ee, v95
	v_exp_f32_e32 v223, v1
	v_exp_f32_e32 v224, v0
	v_cvt_pk_bf16_f32 v248, v209, v210
	v_cvt_pk_bf16_f32 v249, v211, v212
	v_cvt_pk_bf16_f32 v250, v213, v214
	v_cvt_pk_bf16_f32 v251, v215, v216
	v_mfma_f32_32x32x16_bf16 v[64:79], v[4:7], v[8:11], v[64:79]
	s_add_i32 s0, s88, 1
	s_nop 0
	v_permlane32_swap_b32_e32 v248, v250
	v_permlane32_swap_b32_e32 v249, v251
	ds_write_b128 v204, v[248:251]
	v_cvt_pk_bf16_f32 v248, v217, v218
	v_cvt_pk_bf16_f32 v249, v219, v220
	v_cvt_pk_bf16_f32 v250, v221, v222
	v_cvt_pk_bf16_f32 v251, v223, v224
	v_mfma_f32_32x32x16_bf16 v[48:63], v[4:7], v[12:15], v[48:63]
	s_cmp_lg_u32 s88, 2
	s_nop 0
	v_permlane32_swap_b32_e32 v248, v250
	v_permlane32_swap_b32_e32 v249, v251
	ds_write_b128 v204, v[248:251] offset:1024
	s_cselect_b32 s28, s0, 0
	s_cmp_ge_i32 s90, s80
	s_cselect_b64 s[2:3], -1, 0
	s_lshl_b32 s98, s80, 6
	s_sub_i32 s98, s98, 64
	s_min_i32 s96, s89, s98
	s_mul_i32 s96, s96, 0x6000
	s_lshl_b32 s97, s28, 15
	s_add_i32 s97, s83, s97
	v_add_u32_e32 v242, s96, v150
	v_add_u32_e32 v243, s96, v154
	v_add_u32_e32 v244, s96, v152
	v_add_u32_e32 v245, s96, v156
	v_add_u32_e32 v246, 0x100, v244
	v_add_u32_e32 v247, 0x100, v245
	s_waitcnt vmcnt(4) lgkmcnt(0)
	s_barrier
.LBB0_180:
	ds_read_b128 v[8:11], v202 offset:0
	v_lshl_add_u32 v208, s29, 15, v180
	ds_read_b128 v[4:7], v202 offset:0x400
	s_sub_i32 s29, s89, 64
	s_sub_i32 s92, s91, 64
	s_sub_i32 s0, s91, 33
	ds_read_b64_tr_b16 v[136:137], v208 offset:0
	s_cmp_gt_i32 s0, s86
	ds_read_b64_tr_b16 v[138:139], v208 offset:0x800
	s_cselect_b64 s[8:9], -1, 0
	s_cmp_lt_i32 s92, s87
	ds_read_b64_tr_b16 v[140:141], v208 offset:0x200
	s_cselect_b64 s[0:1], -1, 0
	s_cmp_ge_i32 s92, s87
	ds_read_b64_tr_b16 v[142:143], v208 offset:0xa00
	s_cselect_b64 s[92:93], -1, 0
	ds_read_b64_tr_b16 v[12:13], v208 offset:0x400
	s_and_b64 vcc, s[8:9], s[92:93]
	ds_read_b64_tr_b16 v[14:15], v208 offset:0xc00
	v_cndmask_b32_e32 v0, 0, v183, vcc
	v_cndmask_b32_e32 v1, 0, v184, vcc
	ds_read_b64_tr_b16 v[132:133], v208 offset:0x600
	v_cndmask_b32_e64 v0, v181, v0, s[8:9]
	v_cndmask_b32_e64 v1, v182, v1, s[8:9]
	v_mov_b32_e32 v2, v3
	ds_read_b64_tr_b16 v[134:135], v208 offset:0xe00
	ds_read_b128 v[226:229], v186 offset:0x4000
	ds_read_b128 v[230:233], v187 offset:0x4000
	ds_read_b128 v[234:237], v188 offset:0x4000
	ds_read_b128 v[238:241], v189 offset:0x4000
	s_nop 1
	v_mfma_f32_32x32x16_bf16 v[80:95], v[128:131], v[0:3], 0
	s_mov_b32 m0, s84
	s_nop 0
	global_load_lds_dwordx4 v242, s[74:75]
	s_waitcnt lgkmcnt(3)
	v_mfma_f32_32x32x16_bf16 v[80:95], v[226:229], v[96:99], v[80:95]
	v_add_f32_e32 v254, 0, v209
	v_add_f32_e32 v254, v210, v254
	ds_read_b128 v[226:229], v186 offset:0x4080
	s_mov_b32 m0, s85
	s_nop 0
	global_load_lds_dwordx4 v243, s[74:75]
	s_waitcnt lgkmcnt(3)
	v_mfma_f32_32x32x16_bf16 v[80:95], v[230:233], v[100:103], v[80:95]
	v_add_f32_e32 v254, v211, v254
	v_add_f32_e32 v254, v212, v254
	ds_read_b128 v[230:233], v187 offset:0x4080
	s_waitcnt lgkmcnt(3)
	v_mfma_f32_32x32x16_bf16 v[80:95], v[234:237], v[104:107], v[80:95]
	v_add_f32_e32 v254, v213, v254
	v_add_f32_e32 v254, v214, v254
	ds_read_b128 v[234:237], v188 offset:0x4080
	s_waitcnt lgkmcnt(3)
	v_mfma_f32_32x32x16_bf16 v[80:95], v[238:241], v[108:111], v[80:95]
	v_add_f32_e32 v254, v215, v254
	v_add_f32_e32 v254, v216, v254
	ds_read_b128 v[238:241], v189 offset:0x4080
	s_waitcnt lgkmcnt(3)
	v_mfma_f32_32x32x16_bf16 v[80:95], v[226:229], v[112:115], v[80:95]
	v_add_f32_e32 v254, v217, v254
	v_add_f32_e32 v254, v218, v254
	s_waitcnt lgkmcnt(2)
	v_mfma_f32_32x32x16_bf16 v[80:95], v[230:233], v[116:119], v[80:95]
	v_add_f32_e32 v254, v219, v254
	v_add_f32_e32 v254, v220, v254
	s_waitcnt lgkmcnt(1)
	v_mfma_f32_32x32x16_bf16 v[80:95], v[234:237], v[120:123], v[80:95]
	v_add_f32_e32 v254, v221, v254
	v_add_f32_e32 v254, v222, v254
	s_waitcnt lgkmcnt(0)
	v_mfma_f32_32x32x16_bf16 v[80:95], v[238:241], v[124:127], v[80:95]
	v_add_f32_e32 v254, v223, v254
	v_add_f32_e32 v254, v224, v254
	v_cvt_f32_u32_e32 v0, s29
	s_and_b64 s[92:93], s[8:9], s[0:1]
	s_mov_b64 s[0:1], -1
	s_andn2_b64 vcc, exec, s[92:93]
	v_sub_f32_e32 v0, v185, v0
	s_cbranch_vccz .LBB0_182
	v_cndmask_b32_e64 v1, -v148, v148, s[8:9]
	v_mul_f32_e32 v1, v0, v1
	s_mov_b64 s[0:1], 0
.LBB0_182:
	s_and_b64 vcc, exec, s[0:1]
	s_cbranch_vccnz .Ldiag_b
.LBB0_184:
	s_waitcnt lgkmcnt(4)
	v_sub_f32_e32 v1, v1, v203
	v_add_f32_e32 v0, v207, v254
	v_mul_f32_e32 v1, 0x3e0293ee, v1
	v_mfma_f32_32x32x16_bf16 v[32:47], v[8:11], v[136:139], v[32:47]
	ds_read_b64_tr_b16 v[136:137], v208 offset:0x1000
	v_fmamk_f32 v2, v80, 0x3e0293ee, v1
	ds_read_b64_tr_b16 v[138:139], v208 offset:0x1800
	v_exp_f32_e32 v2, v2
	v_fmamk_f32 v81, v81, 0x3e0293ee, v1
	v_exp_f32_e32 v159, v81
	v_add_f32_e32 v80, 0, v2
	v_mfma_f32_32x32x16_bf16 v[16:31], v[8:11], v[140:143], v[16:31]
	ds_read_b64_tr_b16 v[140:141], v208 offset:0x1200
	ds_read_b64_tr_b16 v[142:143], v208 offset:0x1a00
	s_waitcnt lgkmcnt(4)
	v_add_f32_e32 v80, v159, v80
	v_mfma_f32_32x32x16_bf16 v[64:79], v[8:11], v[12:15], v[64:79]
	v_mfma_f32_32x32x16_bf16 v[48:63], v[8:11], v[132:135], v[48:63]
	s_mov_b32 m0, s97
	s_nop 0
	global_load_lds_dwordx4 v244, s[76:77]
	v_fmamk_f32 v8, v82, 0x3e0293ee, v1
	v_exp_f32_e32 v209, v8
	v_fmamk_f32 v9, v83, 0x3e0293ee, v1
	v_exp_f32_e32 v210, v9
	v_add_f32_e32 v8, v209, v80
	v_add_f32_e32 v132, v210, v8
	ds_read_b128 v[8:11], v202 offset:0x800
	ds_read_b64_tr_b16 v[12:13], v208 offset:0x1400
	ds_read_b64_tr_b16 v[14:15], v208 offset:0x1c00
	ds_read_b64_tr_b16 v[80:81], v208 offset:0x1600
	ds_read_b64_tr_b16 v[82:83], v208 offset:0x1e00
	s_waitcnt lgkmcnt(5)
	v_fmamk_f32 v84, v84, 0x3e0293ee, v1
	v_mfma_f32_32x32x16_bf16 v[16:31], v[4:7], v[140:143], v[16:31]
	v_exp_f32_e32 v140, v84
	v_fmamk_f32 v85, v85, 0x3e0293ee, v1
	v_exp_f32_e32 v141, v85
	v_add_f32_e32 v84, v140, v132
	ds_read_b64_tr_b16 v[132:133], v208 offset:0x2000
	ds_read_b64_tr_b16 v[134:135], v208 offset:0x2800
	v_mfma_f32_32x32x16_bf16 v[32:47], v[4:7], v[136:139], v[32:47]
	s_add_i32 m0, s97, 0x400
	s_nop 0
	global_load_lds_dwordx4 v245, s[76:77]
	ds_read_b64_tr_b16 v[136:137], v208 offset:0x2200
	ds_read_b64_tr_b16 v[138:139], v208 offset:0x2a00
	s_waitcnt lgkmcnt(4)
	v_add_f32_e32 v84, v141, v84
	v_mfma_f32_32x32x16_bf16 v[64:79], v[4:7], v[12:15], v[64:79]
	v_mfma_f32_32x32x16_bf16 v[48:63], v[4:7], v[80:83], v[48:63]
	s_add_i32 m0, s97, 0x4000
	s_nop 0
	global_load_lds_dwordx4 v246, s[76:77]
	v_fmamk_f32 v4, v86, 0x3e0293ee, v1
	v_exp_f32_e32 v142, v4
	v_fmamk_f32 v5, v87, 0x3e0293ee, v1
	v_exp_f32_e32 v143, v5
	v_add_f32_e32 v4, v142, v84
	v_add_f32_e32 v84, v143, v4
	ds_read_b128 v[4:7], v202 offset:0xc00
	ds_read_b64_tr_b16 v[12:13], v208 offset:0x2400
	ds_read_b64_tr_b16 v[14:15], v208 offset:0x2c00
	ds_read_b64_tr_b16 v[80:81], v208 offset:0x2600
	ds_read_b64_tr_b16 v[82:83], v208 offset:0x2e00
	s_waitcnt lgkmcnt(5)
	v_fmamk_f32 v85, v88, 0x3e0293ee, v1
	v_exp_f32_e32 v88, v85
	v_fmamk_f32 v85, v89, 0x3e0293ee, v1
	v_exp_f32_e32 v89, v85
	v_mfma_f32_32x32x16_bf16 v[32:47], v[8:11], v[132:135], v[32:47]
	v_add_f32_e32 v84, v88, v84
	v_mfma_f32_32x32x16_bf16 v[16:31], v[8:11], v[136:139], v[16:31]
	s_add_i32 m0, s97, 0x4400
	s_nop 0
	global_load_lds_dwordx4 v247, s[76:77]
	v_add_f32_e32 v136, v89, v84
	ds_read_b64_tr_b16 v[84:85], v208 offset:0x3000
	ds_read_b64_tr_b16 v[86:87], v208 offset:0x3800
	ds_read_b64_tr_b16 v[132:133], v208 offset:0x3200
	ds_read_b64_tr_b16 v[134:135], v208 offset:0x3a00
	s_waitcnt lgkmcnt(4)
	v_mfma_f32_32x32x16_bf16 v[64:79], v[8:11], v[12:15], v[64:79]
	v_mfma_f32_32x32x16_bf16 v[48:63], v[8:11], v[80:83], v[48:63]
	v_fmamk_f32 v8, v90, 0x3e0293ee, v1
	v_exp_f32_e32 v80, v8
	v_fmamk_f32 v9, v91, 0x3e0293ee, v1
	v_exp_f32_e32 v81, v9
	v_add_f32_e32 v8, v80, v136
	v_add_f32_e32 v82, v81, v8
	ds_read_b64_tr_b16 v[8:9], v208 offset:0x3400
	ds_read_b64_tr_b16 v[10:11], v208 offset:0x3c00
	ds_read_b64_tr_b16 v[12:13], v208 offset:0x3600
	ds_read_b64_tr_b16 v[14:15], v208 offset:0x3e00
	s_waitcnt lgkmcnt(4)
	v_mfma_f32_32x32x16_bf16 v[32:47], v[4:7], v[84:87], v[32:47]
	v_fmamk_f32 v83, v92, 0x3e0293ee, v1
	v_exp_f32_e32 v83, v83
	v_fmamk_f32 v84, v93, 0x3e0293ee, v1
	v_exp_f32_e32 v84, v84
	s_waitcnt lgkmcnt(0)
	v_add_f32_e32 v82, v83, v82
	v_add_f32_e32 v82, v84, v82
	v_mfma_f32_32x32x16_bf16 v[16:31], v[4:7], v[132:135], v[16:31]
	v_cvt_pk_bf16_f32 v248, v2, v159
	v_cvt_pk_bf16_f32 v249, v209, v210
	v_cvt_pk_bf16_f32 v250, v140, v141
	v_cvt_pk_bf16_f32 v251, v142, v143
	v_mfma_f32_32x32x16_bf16 v[64:79], v[4:7], v[8:11], v[64:79]
	s_add_i32 s0, s28, 1
	s_cmp_lg_u32 s28, 2
	s_cselect_b32 s1, s0, 0
	s_addk_i32 s89, 0x80
	s_add_i32 s90, s90, 2
	s_and_b64 vcc, exec, s[2:3]
	v_permlane32_swap_b32_e32 v248, v250
	v_permlane32_swap_b32_e32 v249, v251
	ds_write_b128 v205, v[248:251]
	v_fmamk_f32 v252, v94, 0x3e0293ee, v1
	v_exp_f32_e32 v253, v252
	v_fmac_f32_e32 v1, 0x3e0293ee, v95
	v_exp_f32_e32 v1, v1
	v_mfma_f32_32x32x16_bf16 v[48:63], v[4:7], v[12:15], v[48:63]
	v_add_f32_e32 v252, v253, v82
	v_add_f32_e32 v252, v1, v252
	v_add_f32_e32 v207, v0, v252
	v_cvt_pk_bf16_f32 v248, v88, v89
	v_cvt_pk_bf16_f32 v249, v80, v81
	v_cvt_pk_bf16_f32 v250, v83, v84
	v_cvt_pk_bf16_f32 v251, v253, v1
	s_nop 1
	v_permlane32_swap_b32_e32 v248, v250
	v_permlane32_swap_b32_e32 v249, v251
	ds_write_b128 v205, v[248:251] offset:1024
	s_waitcnt vmcnt(4) lgkmcnt(0)
	s_cbranch_vccnz .Lattn_exit
	s_mov_b32 s0, s88
	s_mov_b32 s29, s28
	s_mov_b32 s88, s1
	s_lshl_b32 s98, s80, 6
	s_sub_i32 s96, s89, 64
	s_sub_i32 s98, s98, 64
	s_min_i32 s96, s96, s98
	s_mul_i32 s96, s96, 0x6000
	s_lshl_b32 s97, s88, 15
	s_add_i32 s97, s83, s97
	v_add_u32_e32 v242, s96, v150
	v_add_u32_e32 v243, s96, v154
	v_add_u32_e32 v244, s96, v152
	v_add_u32_e32 v245, s96, v156
	v_add_u32_e32 v246, 0x100, v244
	v_add_u32_e32 v247, 0x100, v245
	s_branch .LBB0_172

.Ldiag_a:
	v_sub_f32_e32 v0, v1, v201
	s_mov_b32 s0, -2.0
	v_add_f32_e32 v1, -1.0, v0
	s_mov_b32 s1, 0xc0400000
	v_pk_add_f32 v[210:211], v[0:1], s[0:1] op_sel_hi:[0,1]
	s_mov_b32 s0, 0xc1000000
	s_mov_b32 s1, 0xc1100000
	v_pk_add_f32 v[212:213], v[0:1], s[0:1] op_sel_hi:[0,1]
	s_mov_b32 s0, 0xc1200000
	s_mov_b32 s1, 0xc1300000
	v_pk_add_f32 v[214:215], v[0:1], s[0:1] op_sel_hi:[0,1]
	s_mov_b32 s0, 0xc1800000
	s_mov_b32 s1, 0xc1880000
	v_pk_add_f32 v[216:217], v[0:1], s[0:1] op_sel_hi:[0,1]
	s_mov_b32 s0, 0xc1900000
	s_mov_b32 s1, 0xc1980000
	v_pk_add_f32 v[218:219], v[0:1], s[0:1] op_sel_hi:[0,1]
	v_pk_add_f32 v[220:221], v[0:1], s[34:35] op_sel_hi:[0,1]
	v_pk_add_f32 v[222:223], v[0:1], s[36:37] op_sel_hi:[0,1]
	v_and_b32_e32 v211, 0x7fffffff, v211
	v_and_b32_e32 v210, 0x7fffffff, v210
	v_and_b32_e32 v213, 0x7fffffff, v213
	v_and_b32_e32 v212, 0x7fffffff, v212
	v_and_b32_e32 v215, 0x7fffffff, v215
	v_and_b32_e32 v214, 0x7fffffff, v214
	v_and_b32_e32 v217, 0x7fffffff, v217
	v_and_b32_e32 v216, 0x7fffffff, v216
	v_and_b32_e32 v219, 0x7fffffff, v219
	v_and_b32_e32 v218, 0x7fffffff, v218
	v_and_b32_e32 v221, 0x7fffffff, v221
	v_and_b32_e32 v220, 0x7fffffff, v220
	v_and_b32_e32 v223, 0x7fffffff, v223
	v_and_b32_e32 v222, 0x7fffffff, v222
	v_and_b32_e32 v0, 0x7fffffff, v0
	v_and_b32_e32 v1, 0x7fffffff, v1
	v_mov_b32_e32 v159, v158
	v_pk_fma_f32 v[94:95], v[158:159], v[222:223], v[94:95]
	v_pk_fma_f32 v[92:93], v[158:159], v[220:221], v[92:93]
	v_pk_fma_f32 v[90:91], v[158:159], v[218:219], v[90:91]
	v_pk_fma_f32 v[88:89], v[158:159], v[216:217], v[88:89]
	v_pk_fma_f32 v[86:87], v[158:159], v[214:215], v[86:87]
	v_pk_fma_f32 v[84:85], v[158:159], v[212:213], v[84:85]
	v_pk_fma_f32 v[82:83], v[158:159], v[210:211], v[82:83]
	v_pk_fma_f32 v[80:81], v[160:161], v[0:1], v[80:81]
	v_mov_b32_e32 v0, 0
	s_branch .LBB0_178
.Ldiag_b:
	v_sub_f32_e32 v0, v0, v201
	s_mov_b32 s0, -2.0
	v_add_f32_e32 v1, -1.0, v0
	s_mov_b32 s1, 0xc0400000
	v_pk_add_f32 v[226:227], v[0:1], s[0:1] op_sel_hi:[0,1]
	s_mov_b32 s0, 0xc1000000
	s_mov_b32 s1, 0xc1100000
	v_pk_add_f32 v[228:229], v[0:1], s[0:1] op_sel_hi:[0,1]
	s_mov_b32 s0, 0xc1200000
	s_mov_b32 s1, 0xc1300000
	v_pk_add_f32 v[230:231], v[0:1], s[0:1] op_sel_hi:[0,1]
	s_mov_b32 s0, 0xc1800000
	s_mov_b32 s1, 0xc1880000
	v_pk_add_f32 v[232:233], v[0:1], s[0:1] op_sel_hi:[0,1]
	s_mov_b32 s0, 0xc1900000
	s_mov_b32 s1, 0xc1980000
	v_pk_add_f32 v[234:235], v[0:1], s[0:1] op_sel_hi:[0,1]
	v_pk_add_f32 v[236:237], v[0:1], s[34:35] op_sel_hi:[0,1]
	v_pk_add_f32 v[238:239], v[0:1], s[36:37] op_sel_hi:[0,1]
	v_and_b32_e32 v227, 0x7fffffff, v227
	v_and_b32_e32 v226, 0x7fffffff, v226
	v_and_b32_e32 v229, 0x7fffffff, v229
	v_and_b32_e32 v228, 0x7fffffff, v228
	v_and_b32_e32 v231, 0x7fffffff, v231
	v_and_b32_e32 v230, 0x7fffffff, v230
	v_and_b32_e32 v233, 0x7fffffff, v233
	v_and_b32_e32 v232, 0x7fffffff, v232
	v_and_b32_e32 v235, 0x7fffffff, v235
	v_and_b32_e32 v234, 0x7fffffff, v234
	v_and_b32_e32 v237, 0x7fffffff, v237
	v_and_b32_e32 v236, 0x7fffffff, v236
	v_and_b32_e32 v239, 0x7fffffff, v239
	v_and_b32_e32 v238, 0x7fffffff, v238
	v_and_b32_e32 v0, 0x7fffffff, v0
	v_and_b32_e32 v1, 0x7fffffff, v1
	v_mov_b32_e32 v159, v158
	v_pk_fma_f32 v[94:95], v[158:159], v[238:239], v[94:95]
	v_pk_fma_f32 v[92:93], v[158:159], v[236:237], v[92:93]
	v_pk_fma_f32 v[90:91], v[158:159], v[234:235], v[90:91]
	v_pk_fma_f32 v[88:89], v[158:159], v[232:233], v[88:89]
	v_pk_fma_f32 v[86:87], v[158:159], v[230:231], v[86:87]
	v_pk_fma_f32 v[84:85], v[158:159], v[228:229], v[84:85]
	v_pk_fma_f32 v[82:83], v[158:159], v[226:227], v[82:83]
	v_pk_fma_f32 v[80:81], v[160:161], v[0:1], v[80:81]
	v_mov_b32_e32 v1, 0
	s_branch .LBB0_184

; __device__ __forceinline__ unsigned rfl(unsigned v) { return (unsigned)__builtin_amdgcn_readfirstlane((int)v); }
; __device__ __forceinline__ void attn_body3(const bf16* __restrict__ Qb, const bf16* __restrict__ Kh, const bf16* __restrict__ Vh,
;                                            bf16* __restrict__ Ob, int seq, int qpos0, float slS, float mraw, char* lds, const int tid) {
;     ...
;   { const int vbp_ = vb0 + vprev * 32768; const char* xr_ = lds + xoff + 16384;
;     { const bf16x8 x_ = *(const bf16x8*)(xr_); pv_ks<0>(o, vbp_, x_); } { const bf16x8 x_ = *(const bf16x8*)(xr_ + 1024); pv_ks<1>(o, vbp_, x_); }
;     { const bf16x8 x_ = *(const bf16x8*)(xr_ + 2048); pv_ks<2>(o, vbp_, x_); } { const bf16x8 x_ = *(const bf16x8*)(xr_ + 3072); pv_ks<3>(o, vbp_, x_); } }
;   { auto rr = __builtin_amdgcn_permlane32_swap(__float_as_uint(lsum), __float_as_uint(lsum), false, false);
;     lsum = __uint_as_float(rr[0]) + __uint_as_float(rr[1]); }
; __global__ __launch_bounds__(512, 2)
; void hybrid_megakernel(Params p_in) {
;     ...
;         for (;;) {
;           __syncthreads();
;           if (tid == 0) *(volatile unsigned*)(shm + A3_X + 8192) = atomicAdd(uctr, 1u);
;           __syncthreads();
;           const int item = (int)rfl(*(volatile unsigned*)(shm + A3_X + 8192));
;           __syncthreads();
;           if (item >= (eightq ? nitems / 8 : nitems)) break;
.LBB0_188:
	v_add_u32_e32 v1, 0x24000, v179
	v_add_u32_e32 v0, s0, v180
	ds_read_b128 v[4:7], v1
	ds_read_b64_tr_b16 v[8:9], v0 offset:0
	ds_read_b64_tr_b16 v[10:11], v0 offset:0x800
	ds_read_b64_tr_b16 v[12:13], v0 offset:0x200
	ds_read_b64_tr_b16 v[14:15], v0 offset:0xa00
	ds_read_b64_tr_b16 v[80:81], v0 offset:0x400
	ds_read_b64_tr_b16 v[82:83], v0 offset:0xc00
	ds_read_b64_tr_b16 v[84:85], v0 offset:0x600
	ds_read_b64_tr_b16 v[86:87], v0 offset:0xe00
	s_waitcnt lgkmcnt(0)
	v_add_u32_e32 v1, 0x24400, v179
	s_waitcnt lgkmcnt(0)
	v_mfma_f32_32x32x16_bf16 v[32:47], v[4:7], v[8:11], v[32:47]
	v_mfma_f32_32x32x16_bf16 v[16:31], v[4:7], v[12:15], v[16:31]
	v_mfma_f32_32x32x16_bf16 v[64:79], v[4:7], v[80:83], v[64:79]
	v_mfma_f32_32x32x16_bf16 v[48:63], v[4:7], v[84:87], v[48:63]
	ds_read_b128 v[4:7], v1
	ds_read_b64_tr_b16 v[8:9], v0 offset:0x1000
	ds_read_b64_tr_b16 v[10:11], v0 offset:0x1800
	ds_read_b64_tr_b16 v[12:13], v0 offset:0x1200
	ds_read_b64_tr_b16 v[14:15], v0 offset:0x1a00
	ds_read_b64_tr_b16 v[80:81], v0 offset:0x1400
	ds_read_b64_tr_b16 v[82:83], v0 offset:0x1c00
	ds_read_b64_tr_b16 v[84:85], v0 offset:0x1600
	ds_read_b64_tr_b16 v[86:87], v0 offset:0x1e00
	s_waitcnt lgkmcnt(0)
	v_add_u32_e32 v1, 0x24800, v179
	s_waitcnt lgkmcnt(0)
	v_mfma_f32_32x32x16_bf16 v[32:47], v[4:7], v[8:11], v[32:47]
	v_mfma_f32_32x32x16_bf16 v[16:31], v[4:7], v[12:15], v[16:31]
	v_mfma_f32_32x32x16_bf16 v[64:79], v[4:7], v[80:83], v[64:79]
	v_mfma_f32_32x32x16_bf16 v[48:63], v[4:7], v[84:87], v[48:63]
	ds_read_b128 v[4:7], v1
	ds_read_b64_tr_b16 v[8:9], v0 offset:0x2000
	ds_read_b64_tr_b16 v[10:11], v0 offset:0x2800
	ds_read_b64_tr_b16 v[12:13], v0 offset:0x2200
	ds_read_b64_tr_b16 v[14:15], v0 offset:0x2a00
	ds_read_b64_tr_b16 v[80:81], v0 offset:0x2400
	ds_read_b64_tr_b16 v[82:83], v0 offset:0x2c00
	ds_read_b64_tr_b16 v[84:85], v0 offset:0x2600
	ds_read_b64_tr_b16 v[86:87], v0 offset:0x2e00
	s_waitcnt lgkmcnt(0)
	v_add_u32_e32 v1, 0x24c00, v179
	s_waitcnt lgkmcnt(0)
	v_mfma_f32_32x32x16_bf16 v[32:47], v[4:7], v[8:11], v[32:47]
	v_mfma_f32_32x32x16_bf16 v[16:31], v[4:7], v[12:15], v[16:31]
	v_mfma_f32_32x32x16_bf16 v[64:79], v[4:7], v[80:83], v[64:79]
	v_mfma_f32_32x32x16_bf16 v[48:63], v[4:7], v[84:87], v[48:63]
	ds_read_b128 v[4:7], v1
	ds_read_b64_tr_b16 v[8:9], v0 offset:0x3000
	ds_read_b64_tr_b16 v[10:11], v0 offset:0x3800
	ds_read_b64_tr_b16 v[12:13], v0 offset:0x3200
	ds_read_b64_tr_b16 v[14:15], v0 offset:0x3a00
	ds_read_b64_tr_b16 v[80:81], v0 offset:0x3400
	ds_read_b64_tr_b16 v[82:83], v0 offset:0x3c00
	ds_read_b64_tr_b16 v[84:85], v0 offset:0x3600
	ds_read_b64_tr_b16 v[86:87], v0 offset:0x3e00
	s_waitcnt lgkmcnt(0)
	s_waitcnt lgkmcnt(0)
	v_mfma_f32_32x32x16_bf16 v[32:47], v[4:7], v[8:11], v[32:47]
	s_lshl_b32 s0, s81, 8
	v_mov_b32_e32 v0, v207
	s_add_i32 s2, s0, 0
	s_nop 0
	v_permlane32_swap_b32_e32 v207, v0
	s_add_i32 s2, s2, 0x20000
	v_mfma_f32_32x32x16_bf16 v[16:31], v[4:7], v[12:15], v[16:31]
	s_waitcnt vmcnt(0)
	s_barrier
	s_mov_b64 s[92:93], exec
	s_and_b64 exec, exec, s[4:5]
	s_cbranch_execz .Lqpf_skip
	v_mov_b32_e32 v254, 1
	global_atomic_add v254, v3, v254, s[68:69] sc0
.Lqpf_skip:
	s_mov_b64 exec, s[92:93]
	s_mov_b32 s99, 1
	v_mfma_f32_32x32x16_bf16 v[64:79], v[4:7], v[80:83], v[64:79]
	v_mfma_f32_32x32x16_bf16 v[48:63], v[4:7], v[84:87], v[48:63]
	s_and_saveexec_b64 s[0:1], s[6:7]
	s_cbranch_execz .LBB0_146
	v_add_f32_e32 v0, v207, v0
	v_lshl_add_u32 v1, v147, 2, s2
	ds_write_b32 v1, v0
	s_branch .LBB0_146
